# ssd_passC second pass with 64 loads in flight, code size kept equal to the previous version so later code keeps its alignment
# speedup vs baseline: 1.0003x; 1.0003x over previous
.LBB0_1056:
	v_mov_b32_dpp v0, v32 row_ror:8 row_mask:0xf bank_mask:0xf bound_ctrl:1
	v_mov_b32_dpp v1, v33 row_ror:8 row_mask:0xf bank_mask:0xf bound_ctrl:1
	v_mov_b32_dpp v2, v16 row_ror:8 row_mask:0xf bank_mask:0xf bound_ctrl:1
	v_mov_b32_dpp v3, v17 row_ror:8 row_mask:0xf bank_mask:0xf bound_ctrl:1
	s_movk_i32 s0, 0xffc0
	v_and_or_b32 v6, v20, s0, v22
	ds_read_b128 v[10:13], v6 offset:46592
	v_pk_add_f32 v[0:1], v[32:33], v[0:1]
	v_pk_add_f32 v[2:3], v[16:17], v[2:3]
	v_lshlrev_b32_e32 v148, 1, v18
	v_readlane_b32 s2, v247, 30
	v_readlane_b32 s3, v247, 31
	v_mov_b32_dpp v6, v0 row_ror:4 row_mask:0xf bank_mask:0xf bound_ctrl:1
	v_mov_b32_dpp v7, v1 row_ror:4 row_mask:0xf bank_mask:0xf bound_ctrl:1
	v_mov_b32_dpp v8, v2 row_ror:4 row_mask:0xf bank_mask:0xf bound_ctrl:1
	v_mov_b32_dpp v9, v3 row_ror:4 row_mask:0xf bank_mask:0xf bound_ctrl:1
	v_pk_add_f32 v[0:1], v[0:1], v[6:7]
	v_pk_add_f32 v[2:3], v[2:3], v[8:9]
	s_mov_b32 s6, 0x3b800000
	s_mov_b32 s4, 0x800000
	v_mov_b32_dpp v6, v0 row_ror:2 row_mask:0xf bank_mask:0xf bound_ctrl:1
	v_mov_b32_dpp v7, v1 row_ror:2 row_mask:0xf bank_mask:0xf bound_ctrl:1
	v_mov_b32_dpp v8, v2 row_ror:2 row_mask:0xf bank_mask:0xf bound_ctrl:1
	v_mov_b32_dpp v9, v3 row_ror:2 row_mask:0xf bank_mask:0xf bound_ctrl:1
	v_pk_add_f32 v[0:1], v[0:1], v[6:7]
	v_pk_add_f32 v[2:3], v[2:3], v[8:9]
	s_mov_b32 s0, 0x358637bd
	v_mov_b32_e32 v4, s0
	v_mov_b32_dpp v6, v0 row_ror:1 row_mask:0xf bank_mask:0xf bound_ctrl:1
	v_mov_b32_dpp v7, v1 row_ror:1 row_mask:0xf bank_mask:0xf bound_ctrl:1
	v_mov_b32_dpp v8, v2 row_ror:1 row_mask:0xf bank_mask:0xf bound_ctrl:1
	v_mov_b32_dpp v9, v3 row_ror:1 row_mask:0xf bank_mask:0xf bound_ctrl:1
	v_pk_add_f32 v[0:1], v[0:1], v[6:7]
	v_pk_add_f32 v[2:3], v[2:3], v[8:9]
	v_fma_f32 v0, v0, s6, v4
	v_fma_f32 v1, v1, s6, v4
	v_fma_f32 v2, v2, s6, v4
	v_fma_f32 v3, v3, s6, v4
	v_cmp_gt_f32_e32 vcc, s4, v0
	v_mul_f32_e32 v6, 0x4b800000, v0
	s_nop 1
	v_cndmask_b32_e32 v0, v0, v6, vcc
	v_rsq_f32_e32 v0, v0
	s_nop 0
	v_mul_f32_e32 v6, 0x45800000, v0
	v_cndmask_b32_e32 v24, v0, v6, vcc
	v_cmp_gt_f32_e32 vcc, s4, v1
	v_mul_f32_e32 v6, 0x4b800000, v1
	s_nop 1
	v_cndmask_b32_e32 v1, v1, v6, vcc
	v_rsq_f32_e32 v1, v1
	s_nop 0
	v_mul_f32_e32 v6, 0x45800000, v1
	v_cndmask_b32_e32 v25, v1, v6, vcc
	v_cmp_gt_f32_e32 vcc, s4, v2
	v_mul_f32_e32 v6, 0x4b800000, v2
	s_nop 1
	v_cndmask_b32_e32 v2, v2, v6, vcc
	v_rsq_f32_e32 v2, v2
	s_nop 0
	v_mul_f32_e32 v6, 0x45800000, v2
	v_cndmask_b32_e32 v26, v2, v6, vcc
	v_cmp_gt_f32_e32 vcc, s4, v3
	v_mul_f32_e32 v6, 0x4b800000, v3
	s_nop 1
	v_cndmask_b32_e32 v3, v3, v6, vcc
	v_rsq_f32_e32 v3, v3
	s_nop 0
	v_mul_f32_e32 v6, 0x45800000, v3
	v_cndmask_b32_e32 v27, v3, v6, vcc
	s_waitcnt lgkmcnt(0)
	v_ashrrev_i32_e32 v15, 31, v10
	v_mov_b32_e32 v14, v10
	v_ashrrev_i32_e32 v19, 31, v11
	v_mov_b32_e32 v18, v11
	v_ashrrev_i32_e32 v21, 31, v12
	v_mov_b32_e32 v20, v12
	v_ashrrev_i32_e32 v23, 31, v13
	v_mov_b32_e32 v22, v13
	v_lshlrev_b64 v[14:15], 11, v[14:15]
	v_lshlrev_b64 v[18:19], 11, v[18:19]
	v_lshlrev_b64 v[20:21], 11, v[20:21]
	v_lshlrev_b64 v[22:23], 11, v[22:23]
	v_lshl_add_u64 v[14:15], s[2:3], 0, v[14:15]
	v_lshl_add_u64 v[18:19], s[2:3], 0, v[18:19]
	v_lshl_add_u64 v[20:21], s[2:3], 0, v[20:21]
	v_lshl_add_u64 v[22:23], s[2:3], 0, v[22:23]
	v_lshl_add_u64 v[14:15], v[14:15], 0, v[148:149]
	v_lshl_add_u64 v[18:19], v[18:19], 0, v[148:149]
	v_lshl_add_u64 v[20:21], v[20:21], 0, v[148:149]
	v_lshl_add_u64 v[22:23], v[22:23], 0, v[148:149]
	global_load_ushort v114, v[14:15], off offset:512
	global_load_ushort v115, v[14:15], off offset:544
	global_load_ushort v116, v[14:15], off offset:576
	global_load_ushort v117, v[14:15], off offset:608
	global_load_ushort v118, v[14:15], off offset:640
	global_load_ushort v119, v[14:15], off offset:672
	global_load_ushort v120, v[14:15], off offset:704
	global_load_ushort v121, v[14:15], off offset:736
	global_load_ushort v122, v[14:15], off offset:768
	global_load_ushort v123, v[14:15], off offset:800
	global_load_ushort v124, v[14:15], off offset:832
	global_load_ushort v125, v[14:15], off offset:864
	global_load_ushort v126, v[14:15], off offset:896
	global_load_ushort v127, v[14:15], off offset:928
	global_load_ushort v128, v[14:15], off offset:960
	global_load_ushort v129, v[14:15], off offset:992
	global_load_ushort v130, v[18:19], off offset:512
	global_load_ushort v131, v[18:19], off offset:544
	global_load_ushort v132, v[18:19], off offset:576
	global_load_ushort v133, v[18:19], off offset:608
	global_load_ushort v134, v[18:19], off offset:640
	global_load_ushort v135, v[18:19], off offset:672
	global_load_ushort v136, v[18:19], off offset:704
	global_load_ushort v137, v[18:19], off offset:736
	global_load_ushort v138, v[18:19], off offset:768
	global_load_ushort v139, v[18:19], off offset:800
	global_load_ushort v140, v[18:19], off offset:832
	global_load_ushort v141, v[18:19], off offset:864
	global_load_ushort v142, v[18:19], off offset:896
	global_load_ushort v143, v[18:19], off offset:928
	global_load_ushort v152, v[18:19], off offset:960
	global_load_ushort v153, v[18:19], off offset:992
	global_load_ushort v154, v[20:21], off offset:512
	global_load_ushort v155, v[20:21], off offset:544
	global_load_ushort v156, v[20:21], off offset:576
	global_load_ushort v157, v[20:21], off offset:608
	global_load_ushort v158, v[20:21], off offset:640
	global_load_ushort v159, v[20:21], off offset:672
	global_load_ushort v160, v[20:21], off offset:704
	global_load_ushort v161, v[20:21], off offset:736
	global_load_ushort v162, v[20:21], off offset:768
	global_load_ushort v163, v[20:21], off offset:800
	global_load_ushort v164, v[20:21], off offset:832
	global_load_ushort v165, v[20:21], off offset:864
	global_load_ushort v166, v[20:21], off offset:896
	global_load_ushort v167, v[20:21], off offset:928
	global_load_ushort v168, v[20:21], off offset:960
	global_load_ushort v169, v[20:21], off offset:992
	global_load_ushort v170, v[22:23], off offset:512
	global_load_ushort v171, v[22:23], off offset:544
	global_load_ushort v204, v[22:23], off offset:576
	global_load_ushort v205, v[22:23], off offset:608
	global_load_ushort v206, v[22:23], off offset:640
	global_load_ushort v207, v[22:23], off offset:672
	global_load_ushort v208, v[22:23], off offset:704
	global_load_ushort v209, v[22:23], off offset:736
	global_load_ushort v210, v[22:23], off offset:768
	global_load_ushort v211, v[22:23], off offset:800
	global_load_ushort v212, v[22:23], off offset:832
	global_load_ushort v213, v[22:23], off offset:864
	global_load_ushort v214, v[22:23], off offset:896
	global_load_ushort v215, v[22:23], off offset:928
	global_load_ushort v216, v[22:23], off offset:960
	global_load_ushort v217, v[22:23], off offset:992
	v_readlane_b32 s80, v247, 59
	v_readlane_b32 s84, v250, 41
	v_readlane_b32 s88, v249, 13
	v_readlane_b32 s90, v247, 63
	v_readlane_b32 s94, v251, 6
	v_readlane_b32 s78, v247, 55
	v_readlane_b32 s26, v249, 25
	v_readlane_b32 s81, v247, 60
	v_readlane_b32 s82, v247, 61
	v_readlane_b32 s83, v247, 62
	v_readlane_b32 s85, v250, 42
	v_readlane_b32 s89, v249, 14
	v_readlane_b32 s91, v251, 0
	v_readlane_b32 s92, v251, 1
	v_readlane_b32 s93, v251, 2
	v_readlane_b32 s95, v251, 7
	v_readlane_b32 s96, v251, 8
	v_readlane_b32 s79, v247, 56
	v_readlane_b32 s97, v251, 9
	s_movk_i32 s87, 0x48
	s_movk_i32 s86, 0xeff
	v_readlane_b32 s27, v249, 26
	v_readlane_b32 s28, v249, 30
	s_waitcnt vmcnt(63)
	v_lshlrev_b32_e32 v114, 16, v114
	v_mul_f32_e32 v114, v24, v114
	v_bfe_u32 v218, v114, 16, 1
	v_add3_u32 v114, v114, v218, s52
	global_store_short_d16_hi v[14:15], v114, off offset:512
	s_waitcnt vmcnt(63)
	v_lshlrev_b32_e32 v115, 16, v115
	v_mul_f32_e32 v115, v24, v115
	v_bfe_u32 v219, v115, 16, 1
	v_add3_u32 v115, v115, v219, s52
	global_store_short_d16_hi v[14:15], v115, off offset:544
	s_waitcnt vmcnt(63)
	v_lshlrev_b32_e32 v116, 16, v116
	v_mul_f32_e32 v116, v24, v116
	v_bfe_u32 v220, v116, 16, 1
	v_add3_u32 v116, v116, v220, s52
	global_store_short_d16_hi v[14:15], v116, off offset:576
	s_waitcnt vmcnt(63)
	v_lshlrev_b32_e32 v117, 16, v117
	v_mul_f32_e32 v117, v24, v117
	v_bfe_u32 v221, v117, 16, 1
	v_add3_u32 v117, v117, v221, s52
	global_store_short_d16_hi v[14:15], v117, off offset:608
	s_waitcnt vmcnt(63)
	v_lshlrev_b32_e32 v118, 16, v118
	v_mul_f32_e32 v118, v24, v118
	v_bfe_u32 v218, v118, 16, 1
	v_add3_u32 v118, v118, v218, s52
	global_store_short_d16_hi v[14:15], v118, off offset:640
	s_waitcnt vmcnt(63)
	v_lshlrev_b32_e32 v119, 16, v119
	v_mul_f32_e32 v119, v24, v119
	v_bfe_u32 v219, v119, 16, 1
	v_add3_u32 v119, v119, v219, s52
	global_store_short_d16_hi v[14:15], v119, off offset:672
	s_waitcnt vmcnt(63)
	v_lshlrev_b32_e32 v120, 16, v120
	v_mul_f32_e32 v120, v24, v120
	v_bfe_u32 v220, v120, 16, 1
	v_add3_u32 v120, v120, v220, s52
	global_store_short_d16_hi v[14:15], v120, off offset:704
	s_waitcnt vmcnt(63)
	v_lshlrev_b32_e32 v121, 16, v121
	v_mul_f32_e32 v121, v24, v121
	v_bfe_u32 v221, v121, 16, 1
	v_add3_u32 v121, v121, v221, s52
	global_store_short_d16_hi v[14:15], v121, off offset:736
	s_waitcnt vmcnt(63)
	v_lshlrev_b32_e32 v122, 16, v122
	v_mul_f32_e32 v122, v24, v122
	v_bfe_u32 v218, v122, 16, 1
	v_add3_u32 v122, v122, v218, s52
	global_store_short_d16_hi v[14:15], v122, off offset:768
	s_waitcnt vmcnt(63)
	v_lshlrev_b32_e32 v123, 16, v123
	v_mul_f32_e32 v123, v24, v123
	v_bfe_u32 v219, v123, 16, 1
	v_add3_u32 v123, v123, v219, s52
	global_store_short_d16_hi v[14:15], v123, off offset:800
	s_waitcnt vmcnt(63)
	v_lshlrev_b32_e32 v124, 16, v124
	v_mul_f32_e32 v124, v24, v124
	v_bfe_u32 v220, v124, 16, 1
	v_add3_u32 v124, v124, v220, s52
	global_store_short_d16_hi v[14:15], v124, off offset:832
	s_waitcnt vmcnt(63)
	v_lshlrev_b32_e32 v125, 16, v125
	v_mul_f32_e32 v125, v24, v125
	v_bfe_u32 v221, v125, 16, 1
	v_add3_u32 v125, v125, v221, s52
	global_store_short_d16_hi v[14:15], v125, off offset:864
	s_waitcnt vmcnt(63)
	v_lshlrev_b32_e32 v126, 16, v126
	v_mul_f32_e32 v126, v24, v126
	v_bfe_u32 v218, v126, 16, 1
	v_add3_u32 v126, v126, v218, s52
	global_store_short_d16_hi v[14:15], v126, off offset:896
	s_waitcnt vmcnt(63)
	v_lshlrev_b32_e32 v127, 16, v127
	v_mul_f32_e32 v127, v24, v127
	v_bfe_u32 v219, v127, 16, 1
	v_add3_u32 v127, v127, v219, s52
	global_store_short_d16_hi v[14:15], v127, off offset:928
	s_waitcnt vmcnt(63)
	v_lshlrev_b32_e32 v128, 16, v128
	v_mul_f32_e32 v128, v24, v128
	v_bfe_u32 v220, v128, 16, 1
	v_add3_u32 v128, v128, v220, s52
	global_store_short_d16_hi v[14:15], v128, off offset:960
	s_waitcnt vmcnt(63)
	v_lshlrev_b32_e32 v129, 16, v129
	v_mul_f32_e32 v129, v24, v129
	v_bfe_u32 v221, v129, 16, 1
	v_add3_u32 v129, v129, v221, s52
	global_store_short_d16_hi v[14:15], v129, off offset:992
	s_waitcnt vmcnt(63)
	v_lshlrev_b32_e32 v130, 16, v130
	v_mul_f32_e32 v130, v25, v130
	v_bfe_u32 v218, v130, 16, 1
	v_add3_u32 v130, v130, v218, s52
	global_store_short_d16_hi v[18:19], v130, off offset:512
	s_waitcnt vmcnt(63)
	v_lshlrev_b32_e32 v131, 16, v131
	v_mul_f32_e32 v131, v25, v131
	v_bfe_u32 v219, v131, 16, 1
	v_add3_u32 v131, v131, v219, s52
	global_store_short_d16_hi v[18:19], v131, off offset:544
	s_waitcnt vmcnt(63)
	v_lshlrev_b32_e32 v132, 16, v132
	v_mul_f32_e32 v132, v25, v132
	v_bfe_u32 v220, v132, 16, 1
	v_add3_u32 v132, v132, v220, s52
	global_store_short_d16_hi v[18:19], v132, off offset:576
	s_waitcnt vmcnt(63)
	v_lshlrev_b32_e32 v133, 16, v133
	v_mul_f32_e32 v133, v25, v133
	v_bfe_u32 v221, v133, 16, 1
	v_add3_u32 v133, v133, v221, s52
	global_store_short_d16_hi v[18:19], v133, off offset:608
	s_waitcnt vmcnt(63)
	v_lshlrev_b32_e32 v134, 16, v134
	v_mul_f32_e32 v134, v25, v134
	v_bfe_u32 v218, v134, 16, 1
	v_add3_u32 v134, v134, v218, s52
	global_store_short_d16_hi v[18:19], v134, off offset:640
	s_waitcnt vmcnt(63)
	v_lshlrev_b32_e32 v135, 16, v135
	v_mul_f32_e32 v135, v25, v135
	v_bfe_u32 v219, v135, 16, 1
	v_add3_u32 v135, v135, v219, s52
	global_store_short_d16_hi v[18:19], v135, off offset:672
	s_waitcnt vmcnt(63)
	v_lshlrev_b32_e32 v136, 16, v136
	v_mul_f32_e32 v136, v25, v136
	v_bfe_u32 v220, v136, 16, 1
	v_add3_u32 v136, v136, v220, s52
	global_store_short_d16_hi v[18:19], v136, off offset:704
	s_waitcnt vmcnt(63)
	v_lshlrev_b32_e32 v137, 16, v137
	v_mul_f32_e32 v137, v25, v137
	v_bfe_u32 v221, v137, 16, 1
	v_add3_u32 v137, v137, v221, s52
	global_store_short_d16_hi v[18:19], v137, off offset:736
	s_waitcnt vmcnt(63)
	v_lshlrev_b32_e32 v138, 16, v138
	v_mul_f32_e32 v138, v25, v138
	v_bfe_u32 v218, v138, 16, 1
	v_add3_u32 v138, v138, v218, s52
	global_store_short_d16_hi v[18:19], v138, off offset:768
	s_waitcnt vmcnt(63)
	v_lshlrev_b32_e32 v139, 16, v139
	v_mul_f32_e32 v139, v25, v139
	v_bfe_u32 v219, v139, 16, 1
	v_add3_u32 v139, v139, v219, s52
	global_store_short_d16_hi v[18:19], v139, off offset:800
	s_waitcnt vmcnt(63)
	v_lshlrev_b32_e32 v140, 16, v140
	v_mul_f32_e32 v140, v25, v140
	v_bfe_u32 v220, v140, 16, 1
	v_add3_u32 v140, v140, v220, s52
	global_store_short_d16_hi v[18:19], v140, off offset:832
	s_waitcnt vmcnt(63)
	v_lshlrev_b32_e32 v141, 16, v141
	v_mul_f32_e32 v141, v25, v141
	v_bfe_u32 v221, v141, 16, 1
	v_add3_u32 v141, v141, v221, s52
	global_store_short_d16_hi v[18:19], v141, off offset:864
	s_waitcnt vmcnt(63)
	v_lshlrev_b32_e32 v142, 16, v142
	v_mul_f32_e32 v142, v25, v142
	v_bfe_u32 v218, v142, 16, 1
	v_add3_u32 v142, v142, v218, s52
	global_store_short_d16_hi v[18:19], v142, off offset:896
	s_waitcnt vmcnt(63)
	v_lshlrev_b32_e32 v143, 16, v143
	v_mul_f32_e32 v143, v25, v143
	v_bfe_u32 v219, v143, 16, 1
	v_add3_u32 v143, v143, v219, s52
	global_store_short_d16_hi v[18:19], v143, off offset:928
	s_waitcnt vmcnt(63)
	v_lshlrev_b32_e32 v152, 16, v152
	v_mul_f32_e32 v152, v25, v152
	v_bfe_u32 v220, v152, 16, 1
	v_add3_u32 v152, v152, v220, s52
	global_store_short_d16_hi v[18:19], v152, off offset:960
	s_waitcnt vmcnt(63)
	v_lshlrev_b32_e32 v153, 16, v153
	v_mul_f32_e32 v153, v25, v153
	v_bfe_u32 v221, v153, 16, 1
	v_add3_u32 v153, v153, v221, s52
	global_store_short_d16_hi v[18:19], v153, off offset:992
	s_waitcnt vmcnt(63)
	v_lshlrev_b32_e32 v154, 16, v154
	v_mul_f32_e32 v154, v26, v154
	v_bfe_u32 v218, v154, 16, 1
	v_add3_u32 v154, v154, v218, s52
	global_store_short_d16_hi v[20:21], v154, off offset:512
	s_waitcnt vmcnt(63)
	v_lshlrev_b32_e32 v155, 16, v155
	v_mul_f32_e32 v155, v26, v155
	v_bfe_u32 v219, v155, 16, 1
	v_add3_u32 v155, v155, v219, s52
	global_store_short_d16_hi v[20:21], v155, off offset:544
	s_waitcnt vmcnt(63)
	v_lshlrev_b32_e32 v156, 16, v156
	v_mul_f32_e32 v156, v26, v156
	v_bfe_u32 v220, v156, 16, 1
	v_add3_u32 v156, v156, v220, s52
	global_store_short_d16_hi v[20:21], v156, off offset:576
	s_waitcnt vmcnt(63)
	v_lshlrev_b32_e32 v157, 16, v157
	v_mul_f32_e32 v157, v26, v157
	v_bfe_u32 v221, v157, 16, 1
	v_add3_u32 v157, v157, v221, s52
	global_store_short_d16_hi v[20:21], v157, off offset:608
	s_waitcnt vmcnt(63)
	v_lshlrev_b32_e32 v158, 16, v158
	v_mul_f32_e32 v158, v26, v158
	v_bfe_u32 v218, v158, 16, 1
	v_add3_u32 v158, v158, v218, s52
	global_store_short_d16_hi v[20:21], v158, off offset:640
	s_waitcnt vmcnt(63)
	v_lshlrev_b32_e32 v159, 16, v159
	v_mul_f32_e32 v159, v26, v159
	v_bfe_u32 v219, v159, 16, 1
	v_add3_u32 v159, v159, v219, s52
	global_store_short_d16_hi v[20:21], v159, off offset:672
	s_waitcnt vmcnt(63)
	v_lshlrev_b32_e32 v160, 16, v160
	v_mul_f32_e32 v160, v26, v160
	v_bfe_u32 v220, v160, 16, 1
	v_add3_u32 v160, v160, v220, s52
	global_store_short_d16_hi v[20:21], v160, off offset:704
	s_waitcnt vmcnt(63)
	v_lshlrev_b32_e32 v161, 16, v161
	v_mul_f32_e32 v161, v26, v161
	v_bfe_u32 v221, v161, 16, 1
	v_add3_u32 v161, v161, v221, s52
	global_store_short_d16_hi v[20:21], v161, off offset:736
	s_waitcnt vmcnt(63)
	v_lshlrev_b32_e32 v162, 16, v162
	v_mul_f32_e32 v162, v26, v162
	v_bfe_u32 v218, v162, 16, 1
	v_add3_u32 v162, v162, v218, s52
	global_store_short_d16_hi v[20:21], v162, off offset:768
	s_waitcnt vmcnt(63)
	v_lshlrev_b32_e32 v163, 16, v163
	v_mul_f32_e32 v163, v26, v163
	v_bfe_u32 v219, v163, 16, 1
	v_add3_u32 v163, v163, v219, s52
	global_store_short_d16_hi v[20:21], v163, off offset:800
	s_waitcnt vmcnt(63)
	v_lshlrev_b32_e32 v164, 16, v164
	v_mul_f32_e32 v164, v26, v164
	v_bfe_u32 v220, v164, 16, 1
	v_add3_u32 v164, v164, v220, s52
	global_store_short_d16_hi v[20:21], v164, off offset:832
	s_waitcnt vmcnt(63)
	v_lshlrev_b32_e32 v165, 16, v165
	v_mul_f32_e32 v165, v26, v165
	v_bfe_u32 v221, v165, 16, 1
	v_add3_u32 v165, v165, v221, s52
	global_store_short_d16_hi v[20:21], v165, off offset:864
	s_waitcnt vmcnt(63)
	v_lshlrev_b32_e32 v166, 16, v166
	v_mul_f32_e32 v166, v26, v166
	v_bfe_u32 v218, v166, 16, 1
	v_add3_u32 v166, v166, v218, s52
	global_store_short_d16_hi v[20:21], v166, off offset:896
	s_waitcnt vmcnt(63)
	v_lshlrev_b32_e32 v167, 16, v167
	v_mul_f32_e32 v167, v26, v167
	v_bfe_u32 v219, v167, 16, 1
	v_add3_u32 v167, v167, v219, s52
	global_store_short_d16_hi v[20:21], v167, off offset:928
	s_waitcnt vmcnt(63)
	v_lshlrev_b32_e32 v168, 16, v168
	v_mul_f32_e32 v168, v26, v168
	v_bfe_u32 v220, v168, 16, 1
	v_add3_u32 v168, v168, v220, s52
	global_store_short_d16_hi v[20:21], v168, off offset:960
	s_waitcnt vmcnt(63)
	v_lshlrev_b32_e32 v169, 16, v169
	v_mul_f32_e32 v169, v26, v169
	v_bfe_u32 v221, v169, 16, 1
	v_add3_u32 v169, v169, v221, s52
	global_store_short_d16_hi v[20:21], v169, off offset:992
	s_waitcnt vmcnt(63)
	v_lshlrev_b32_e32 v170, 16, v170
	v_mul_f32_e32 v170, v27, v170
	v_bfe_u32 v218, v170, 16, 1
	v_add3_u32 v170, v170, v218, s52
	global_store_short_d16_hi v[22:23], v170, off offset:512
	s_waitcnt vmcnt(63)
	v_lshlrev_b32_e32 v171, 16, v171
	v_mul_f32_e32 v171, v27, v171
	v_bfe_u32 v219, v171, 16, 1
	v_add3_u32 v171, v171, v219, s52
	global_store_short_d16_hi v[22:23], v171, off offset:544
	s_waitcnt vmcnt(63)
	v_lshlrev_b32_e32 v204, 16, v204
	v_mul_f32_e32 v204, v27, v204
	v_bfe_u32 v220, v204, 16, 1
	v_add3_u32 v204, v204, v220, s52
	global_store_short_d16_hi v[22:23], v204, off offset:576
	s_waitcnt vmcnt(63)
	v_lshlrev_b32_e32 v205, 16, v205
	v_mul_f32_e32 v205, v27, v205
	v_bfe_u32 v221, v205, 16, 1
	v_add3_u32 v205, v205, v221, s52
	global_store_short_d16_hi v[22:23], v205, off offset:608
	s_waitcnt vmcnt(63)
	v_lshlrev_b32_e32 v206, 16, v206
	v_mul_f32_e32 v206, v27, v206
	v_bfe_u32 v218, v206, 16, 1
	v_add3_u32 v206, v206, v218, s52
	global_store_short_d16_hi v[22:23], v206, off offset:640
	s_waitcnt vmcnt(63)
	v_lshlrev_b32_e32 v207, 16, v207
	v_mul_f32_e32 v207, v27, v207
	v_bfe_u32 v219, v207, 16, 1
	v_add3_u32 v207, v207, v219, s52
	global_store_short_d16_hi v[22:23], v207, off offset:672
	s_waitcnt vmcnt(63)
	v_lshlrev_b32_e32 v208, 16, v208
	v_mul_f32_e32 v208, v27, v208
	v_bfe_u32 v220, v208, 16, 1
	v_add3_u32 v208, v208, v220, s52
	global_store_short_d16_hi v[22:23], v208, off offset:704
	s_waitcnt vmcnt(63)
	v_lshlrev_b32_e32 v209, 16, v209
	v_mul_f32_e32 v209, v27, v209
	v_bfe_u32 v221, v209, 16, 1
	v_add3_u32 v209, v209, v221, s52
	global_store_short_d16_hi v[22:23], v209, off offset:736
	s_waitcnt vmcnt(63)
	v_lshlrev_b32_e32 v210, 16, v210
	v_mul_f32_e32 v210, v27, v210
	v_bfe_u32 v218, v210, 16, 1
	v_add3_u32 v210, v210, v218, s52
	global_store_short_d16_hi v[22:23], v210, off offset:768
	s_waitcnt vmcnt(63)
	v_lshlrev_b32_e32 v211, 16, v211
	v_mul_f32_e32 v211, v27, v211
	v_bfe_u32 v219, v211, 16, 1
	v_add3_u32 v211, v211, v219, s52
	global_store_short_d16_hi v[22:23], v211, off offset:800
	s_waitcnt vmcnt(63)
	v_lshlrev_b32_e32 v212, 16, v212
	v_mul_f32_e32 v212, v27, v212
	v_bfe_u32 v220, v212, 16, 1
	v_add3_u32 v212, v212, v220, s52
	global_store_short_d16_hi v[22:23], v212, off offset:832
	s_waitcnt vmcnt(63)
	v_lshlrev_b32_e32 v213, 16, v213
	v_mul_f32_e32 v213, v27, v213
	v_bfe_u32 v221, v213, 16, 1
	v_add3_u32 v213, v213, v221, s52
	global_store_short_d16_hi v[22:23], v213, off offset:864
	s_waitcnt vmcnt(63)
	v_lshlrev_b32_e32 v214, 16, v214
	v_mul_f32_e32 v214, v27, v214
	v_bfe_u32 v218, v214, 16, 1
	v_add3_u32 v214, v214, v218, s52
	global_store_short_d16_hi v[22:23], v214, off offset:896
	s_waitcnt vmcnt(63)
	v_lshlrev_b32_e32 v215, 16, v215
	v_mul_f32_e32 v215, v27, v215
	v_bfe_u32 v219, v215, 16, 1
	v_add3_u32 v215, v215, v219, s52
	global_store_short_d16_hi v[22:23], v215, off offset:928
	s_waitcnt vmcnt(63)
	v_lshlrev_b32_e32 v216, 16, v216
	v_mul_f32_e32 v216, v27, v216
	v_bfe_u32 v220, v216, 16, 1
	v_add3_u32 v216, v216, v220, s52
	global_store_short_d16_hi v[22:23], v216, off offset:960
	s_waitcnt vmcnt(63)
	v_lshlrev_b32_e32 v217, 16, v217
	v_mul_f32_e32 v217, v27, v217
	v_bfe_u32 v221, v217, 16, 1
	v_add3_u32 v217, v217, v221, s52
	global_store_short_d16_hi v[22:23], v217, off offset:992
